# attention step NT-2: waves 0..3 (key tile wholly above their rows) only issue their V DMA share and rendezvous; waves 0,1 then finish, waves 2,3 finish with one closing PV of the previous tile
# speedup vs baseline: 1.0024x; 1.0024x over previous
; template <int THRL> __device__ __forceinline__ void attn_unit(int b, int h, int qb, const f16_t* Q, const f16_t* __restrict__ K, const f16_t* __restrict__ V, f16_t* O, const float* __restrict__ kms, char* shm) {
;     ...
;     { auto rr = __builtin_amdgcn_permlane32_swap(__float_as_uint(l_reg), __float_as_uint(l_reg), false, false); l_reg = __uint_as_float(rr[0]) + __uint_as_float(rr[1]); }
;     if (hi == 0) wsf[32 + r32] = l_reg; asm volatile("s_waitcnt lgkmcnt(0)" ::: "memory");
.Lattn_fin_skip03:
	v_mov_b32_e32 v51, v214
	v_lshl_add_u32 v50, v204, 4, s88
	v_cmp_gt_u32_e32 vcc, 32, v201
	v_mov_b32_e32 v34, v51
	s_nop 1
	v_permlane32_swap_b32_e32 v51, v34
	s_and_saveexec_b64 s[2:3], vcc
	s_cbranch_execz .LBB0_529
	v_add_f32_e32 v34, v51, v34
	ds_write_b32 v207, v34 offset:49280
	s_branch .LBB0_529

; #define SBAR() __builtin_amdgcn_sched_barrier(0)
; #define RESC() do { if (resc) { asm volatile("s_waitcnt lgkmcnt(0)" ::: "memory"); \
;       _Pragma("unroll") for (int d_ = 0; d_ < 2; ++d_) _Pragma("unroll") for (int r = 0; r < 16; ++r) o[d_][r] *= wsf[crow(r, hi)]; } } while (0)
; #define ROT() do { sl_prev = sl_cur; sl_cur = sl_next; sl_next = (sl_next == (NSLOT - 1) * SLOTB) ? 0 : sl_next + SLOTB; } while (0)
; #define PKW(P, B) pkh(P[B], P[B + 1])
; #define ENDW(tt) do { if ((tt) + 3 < NT) { WAIT_BAR(2); } else if ((tt) + 2 < NT) { WAIT_BAR(1); } else { WAIT_BAR(0); } } while (0)
; template <int THRL> __device__ __forceinline__ void attn_unit(int b, int h, int qb, const f16_t* Q, const f16_t* __restrict__ K, const f16_t* __restrict__ V, f16_t* O, const float* __restrict__ kms, char* shm) {
;     ...
;     for (; t + 1 < NT; t += 2) {
;         STEP(pB0, pB1, pA0, pA1, t, (t + 3 < NT), (t + 1 < NT), (t + 1 < NT));         ENDW(t);     RESC(); ROT();
;         STEP(pA0, pA1, pB0, pB1, t + 1, (t + 4 < NT), (t + 2 < NT), (t + 2 < NT));     ENDW(t + 1); RESC(); ROT();
;     }
;     STEP(pB0, pB1, pA0, pA1, NT - 1, false, false, false); RESC();
;     { float sacc = pB0[0] + pB0[1]; _Pragma("unroll") for (int r = 2; r < 16; ++r) sacc += pB0[r]; _Pragma("unroll") for (int r = 0; r < 16; ++r) sacc += pB1[r]; l_reg += sacc;
;       pw0 = (u32x4){PKW(pB0, 0), PKW(pB0, 2), PKW(pB0, 4), PKW(pB0, 6)}; pw1 = (u32x4){PKW(pB0, 8), PKW(pB0, 10), PKW(pB0, 12), PKW(pB0, 14)}; pw2 = (u32x4){PKW(pB1, 0), PKW(pB1, 2), PKW(pB1, 4), PKW(pB1, 6)}; pw3 = (u32x4){PKW(pB1, 8), PKW(pB1, 10), PKW(pB1, 12), PKW(pB1, 14)};
;       SBAR(); pv(o, vb0 + sl_cur, PAF(0), PAF(1), PAF(2), PAF(3)); }
.LBB0_585:
	s_add_i32 s98, s40, 3
	s_cmp_lg_u32 s98, s35
	s_cbranch_scc1 .Lattn_ts2_full
	s_cmp_gt_u32 s29, 3
	s_cbranch_scc1 .Lattn_ts2_full
	s_add_i32 s98, s68, 0x2000
	s_cmpk_lg_i32 s68, 0x4000
	s_cselect_b32 s98, s98, 0
	v_lshl_add_u64 v[216:217], v[192:193], 0, s[42:43]
	s_add_i32 s98, s98, s77
	s_mov_b32 s99, m0
	s_mov_b32 m0, s98
	s_nop 0
	global_load_lds_dwordx4 v[216:217], off
	s_mov_b32 m0, s99
	s_waitcnt vmcnt(0) lgkmcnt(0)
	s_barrier
	s_cmp_gt_u32 s29, 1
	s_cbranch_scc0 .Lattn_fin_skip03
	v_mov_b64_e32 v[34:35], v[82:83]
	v_mov_b64_e32 v[36:37], v[84:85]
	v_mov_b64_e32 v[38:39], v[86:87]
	v_mov_b64_e32 v[40:41], v[88:89]
	v_mov_b64_e32 v[42:43], v[90:91]
	v_mov_b64_e32 v[44:45], v[92:93]
	v_mov_b64_e32 v[46:47], v[94:95]
	v_mov_b64_e32 v[48:49], v[96:97]
	v_mov_b64_e32 v[82:83], v[98:99]
	v_mov_b64_e32 v[84:85], v[100:101]
	v_mov_b64_e32 v[86:87], v[102:103]
	v_mov_b64_e32 v[88:89], v[104:105]
	v_mov_b64_e32 v[90:91], v[106:107]
	v_mov_b64_e32 v[92:93], v[108:109]
	v_mov_b64_e32 v[94:95], v[110:111]
	v_mov_b64_e32 v[96:97], v[112:113]
	v_mov_b32_e32 v114, v214
	v_lshl_add_u32 v50, v204, 4, s88
	s_branch .LBB0_565
